# FF1 epilogue squares as v_pk_mul_f32 (8 instead of 16 per row) plus the straight-line paired-store path for in-proj row-major tiles, on top of the phase-start-stagger version
# baseline (speedup 1.0000x reference)
;     __device__ __forceinline__ void fin(int m, int n, f32x4 v, f32x4, f32x4) const { horiz(m, n, v); }
;     __device__ __forceinline__ void fin(int m, int n, f32x4 v, f32x4, f32x4) const { horiz(m, n, v); }
; template <int MI, bool SWAP, class Epi> ...
;     ...
;     if (SWAP) {
; #pragma unroll
;         for (int i2 = 0; i2 < MI / 2; ++i2) {
;             f32x4 pa[2][4], pg[2][4];
; #pragma unroll
;             for (int ii = 0; ii < 2; ++ii)
; #pragma unroll
;                 for (int j = 0; j < 4; ++j) epi.pre(m0 + wr * (MI * 16) + (i2 * 2 + ii) * 16 + fr, n0 + wc * 64 + j * 16 + fq * 4, pa[ii][j], pg[ii][j]);
;             __builtin_amdgcn_sched_barrier(0);
; #pragma unroll
;             for (int ii = 0; ii < 2; ++ii)
; #pragma unroll
;                 for (int j = 0; j < 4; ++j) epi.fin(m0 + wr * (MI * 16) + (i2 * 2 + ii) * 16 + fr, n0 + wc * 64 + j * 16 + fq * 4, acc[i2 * 2 + ii][j], pa[ii][j], pg[ii][j]);
;         }
;     __device__ __forceinline__ void horiz(int m, int n, f32x4 v) const {
;         float a = fmaxf(v[0], 0.f), b = fmaxf(v[1], 0.f), c = fmaxf(v[2], 0.f), d = fmaxf(v[3], 0.f);
;         u32x2 w; w.x = pack2(a * a, b * b); w.y = pack2(c * c, d * d);
;         *(u32x2*)(HID + (size_t)m * DFF + n) = w;
;     }
.LBB0_2163:
	v_or_b32_e32 v128, s11, v221
	v_lshl_or_b32 v129, v218, 2, s10
	v_add_u32_e32 v128, s25, v128
	v_or_b32_e32 v130, s26, v129
	v_ashrrev_i32_e32 v129, 31, v128
	v_lshlrev_b64 v[132:133], 13, v[128:129]
	v_ashrrev_i32_e32 v131, 31, v130
	v_lshl_add_u64 v[132:133], s[68:69], 0, v[132:133]
	v_lshlrev_b64 v[128:129], 1, v[130:131]
	v_lshl_add_u64 v[130:131], v[132:133], 0, v[128:129]
	v_and_b32_e32 v128, 1, v218
	v_mul_u32_u24_e32 v128, 24, v128
	v_mov_b32_e32 v129, 0
	v_lshl_add_u64 v[130:131], v[130:131], 0, v[128:129]
	s_mov_b64 vcc, 0x20000
	v_writelane_b32 v253, s56, 47
	v_writelane_b32 v253, s55, 48
	v_max_f32_e32 v112, v112, v112
	v_max_f32_e32 v113, v113, v113
	v_max_f32_e32 v114, v114, v114
	v_max_f32_e32 v115, v115, v115
	v_max_f32_e32 v116, v116, v116
	v_max_f32_e32 v117, v117, v117
	v_max_f32_e32 v118, v118, v118
	v_max_f32_e32 v119, v119, v119
	v_max_f32_e32 v120, v120, v120
	v_max_f32_e32 v121, v121, v121
	v_max_f32_e32 v122, v122, v122
	v_max_f32_e32 v123, v123, v123
	v_max_f32_e32 v124, v124, v124
	v_max_f32_e32 v125, v125, v125
	v_max_f32_e32 v126, v126, v126
	v_max_f32_e32 v127, v127, v127
	v_max_f32_e32 v112, 0, v112
	v_max_f32_e32 v113, 0, v113
	v_max_f32_e32 v114, 0, v114
	v_max_f32_e32 v115, 0, v115
	v_max_f32_e32 v116, 0, v116
	v_max_f32_e32 v117, 0, v117
	v_max_f32_e32 v118, 0, v118
	v_max_f32_e32 v119, 0, v119
	v_max_f32_e32 v120, 0, v120
	v_max_f32_e32 v121, 0, v121
	v_max_f32_e32 v122, 0, v122
	v_max_f32_e32 v123, 0, v123
	v_max_f32_e32 v124, 0, v124
	v_max_f32_e32 v125, 0, v125
	v_max_f32_e32 v126, 0, v126
	v_max_f32_e32 v127, 0, v127
	v_pk_mul_f32 v[112:113], v[112:113], v[112:113]
	v_pk_mul_f32 v[114:115], v[114:115], v[114:115]
	v_pk_mul_f32 v[116:117], v[116:117], v[116:117]
	v_pk_mul_f32 v[118:119], v[118:119], v[118:119]
	v_pk_mul_f32 v[120:121], v[120:121], v[120:121]
	v_pk_mul_f32 v[122:123], v[122:123], v[122:123]
	v_pk_mul_f32 v[124:125], v[124:125], v[124:125]
	v_pk_mul_f32 v[126:127], v[126:127], v[126:127]
	v_cvt_pk_bf16_f32 v124, v124, v125
	v_cvt_pk_bf16_f32 v125, v126, v127
	v_cvt_pk_bf16_f32 v126, v120, v121
	v_cvt_pk_bf16_f32 v127, v122, v123
	v_cvt_pk_bf16_f32 v116, v116, v117
	v_cvt_pk_bf16_f32 v117, v118, v119
	v_cvt_pk_bf16_f32 v118, v112, v113
	v_cvt_pk_bf16_f32 v119, v114, v115
	s_nop 1
	v_permlane16_swap_b32_e32 v124, v126
	v_permlane16_swap_b32_e32 v125, v127
	v_permlane16_swap_b32_e32 v116, v118
	v_permlane16_swap_b32_e32 v117, v119
	v_lshl_add_u64 v[132:133], v[130:131], 0, vcc
	s_nop 0
	global_store_dwordx4 v[130:131], v[124:127], off
	global_store_dwordx4 v[130:131], v[116:119], off offset:64
	v_max_f32_e32 v96, v96, v96
	v_max_f32_e32 v97, v97, v97
	v_max_f32_e32 v98, v98, v98
	v_max_f32_e32 v99, v99, v99
	v_max_f32_e32 v100, v100, v100
	v_max_f32_e32 v101, v101, v101
	v_max_f32_e32 v102, v102, v102
	v_max_f32_e32 v103, v103, v103
	v_max_f32_e32 v104, v104, v104
	v_max_f32_e32 v105, v105, v105
	v_max_f32_e32 v106, v106, v106
	v_max_f32_e32 v107, v107, v107
	v_max_f32_e32 v108, v108, v108
	v_max_f32_e32 v109, v109, v109
	v_max_f32_e32 v110, v110, v110
	v_max_f32_e32 v111, v111, v111
	v_max_f32_e32 v96, 0, v96
	v_max_f32_e32 v97, 0, v97
	v_max_f32_e32 v98, 0, v98
	v_max_f32_e32 v99, 0, v99
	v_max_f32_e32 v100, 0, v100
	v_max_f32_e32 v101, 0, v101
	v_max_f32_e32 v102, 0, v102
	v_max_f32_e32 v103, 0, v103
	v_max_f32_e32 v104, 0, v104
	v_max_f32_e32 v105, 0, v105
	v_max_f32_e32 v106, 0, v106
	v_max_f32_e32 v107, 0, v107
	v_max_f32_e32 v108, 0, v108
	v_max_f32_e32 v109, 0, v109
	v_max_f32_e32 v110, 0, v110
	v_max_f32_e32 v111, 0, v111
	v_pk_mul_f32 v[96:97], v[96:97], v[96:97]
	v_pk_mul_f32 v[98:99], v[98:99], v[98:99]
	v_pk_mul_f32 v[100:101], v[100:101], v[100:101]
	v_pk_mul_f32 v[102:103], v[102:103], v[102:103]
	v_pk_mul_f32 v[104:105], v[104:105], v[104:105]
	v_pk_mul_f32 v[106:107], v[106:107], v[106:107]
	v_pk_mul_f32 v[108:109], v[108:109], v[108:109]
	v_pk_mul_f32 v[110:111], v[110:111], v[110:111]
	v_cvt_pk_bf16_f32 v108, v108, v109
	v_cvt_pk_bf16_f32 v109, v110, v111
	v_cvt_pk_bf16_f32 v110, v104, v105
	v_cvt_pk_bf16_f32 v111, v106, v107
	v_cvt_pk_bf16_f32 v100, v100, v101
	v_cvt_pk_bf16_f32 v101, v102, v103
	v_cvt_pk_bf16_f32 v102, v96, v97
	v_cvt_pk_bf16_f32 v103, v98, v99
	s_nop 1
	v_permlane16_swap_b32_e32 v108, v110
	v_permlane16_swap_b32_e32 v109, v111
	v_permlane16_swap_b32_e32 v100, v102
	v_permlane16_swap_b32_e32 v101, v103
	v_lshl_add_u64 v[130:131], v[132:133], 0, vcc
	s_nop 0
	global_store_dwordx4 v[132:133], v[108:111], off
	global_store_dwordx4 v[132:133], v[100:103], off offset:64
	v_max_f32_e32 v80, v80, v80
	v_max_f32_e32 v81, v81, v81
	v_max_f32_e32 v82, v82, v82
	v_max_f32_e32 v83, v83, v83
	v_max_f32_e32 v84, v84, v84
	v_max_f32_e32 v85, v85, v85
	v_max_f32_e32 v86, v86, v86
	v_max_f32_e32 v87, v87, v87
	v_max_f32_e32 v88, v88, v88
	v_max_f32_e32 v89, v89, v89
	v_max_f32_e32 v90, v90, v90
	v_max_f32_e32 v91, v91, v91
	v_max_f32_e32 v92, v92, v92
	v_max_f32_e32 v93, v93, v93
	v_max_f32_e32 v94, v94, v94
	v_max_f32_e32 v95, v95, v95
	v_max_f32_e32 v80, 0, v80
	v_max_f32_e32 v81, 0, v81
	v_max_f32_e32 v82, 0, v82
	v_max_f32_e32 v83, 0, v83
	v_max_f32_e32 v84, 0, v84
	v_max_f32_e32 v85, 0, v85
	v_max_f32_e32 v86, 0, v86
	v_max_f32_e32 v87, 0, v87
	v_max_f32_e32 v88, 0, v88
	v_max_f32_e32 v89, 0, v89
	v_max_f32_e32 v90, 0, v90
	v_max_f32_e32 v91, 0, v91
	v_max_f32_e32 v92, 0, v92
	v_max_f32_e32 v93, 0, v93
	v_max_f32_e32 v94, 0, v94
	v_max_f32_e32 v95, 0, v95
	v_pk_mul_f32 v[80:81], v[80:81], v[80:81]
	v_pk_mul_f32 v[82:83], v[82:83], v[82:83]
	v_pk_mul_f32 v[84:85], v[84:85], v[84:85]
	v_pk_mul_f32 v[86:87], v[86:87], v[86:87]
	v_pk_mul_f32 v[88:89], v[88:89], v[88:89]
;     __device__ __forceinline__ void horiz(int m, int n, f32x4 v) const {
;         float a = fmaxf(v[0], 0.f), b = fmaxf(v[1], 0.f), c = fmaxf(v[2], 0.f), d = fmaxf(v[3], 0.f);
;         u32x2 w; w.x = pack2(a * a, b * b); w.y = pack2(c * c, d * d);
;         *(u32x2*)(HID + (size_t)m * DFF + n) = w;
;     }
	v_pk_mul_f32 v[90:91], v[90:91], v[90:91]
	v_pk_mul_f32 v[92:93], v[92:93], v[92:93]
	v_pk_mul_f32 v[94:95], v[94:95], v[94:95]
	v_cvt_pk_bf16_f32 v92, v92, v93
	v_cvt_pk_bf16_f32 v93, v94, v95
	v_cvt_pk_bf16_f32 v94, v88, v89
	v_cvt_pk_bf16_f32 v95, v90, v91
	v_cvt_pk_bf16_f32 v84, v84, v85
	v_cvt_pk_bf16_f32 v85, v86, v87
	v_cvt_pk_bf16_f32 v86, v80, v81
	v_cvt_pk_bf16_f32 v87, v82, v83
	s_nop 1
	v_permlane16_swap_b32_e32 v92, v94
	v_permlane16_swap_b32_e32 v93, v95
	v_permlane16_swap_b32_e32 v84, v86
	v_permlane16_swap_b32_e32 v85, v87
	v_lshl_add_u64 v[132:133], v[130:131], 0, vcc
	s_nop 0
	global_store_dwordx4 v[130:131], v[92:95], off
	global_store_dwordx4 v[130:131], v[84:87], off offset:64
	v_max_f32_e32 v64, v64, v64
	v_max_f32_e32 v65, v65, v65
	v_max_f32_e32 v66, v66, v66
	v_max_f32_e32 v67, v67, v67
	v_max_f32_e32 v68, v68, v68
	v_max_f32_e32 v69, v69, v69
	v_max_f32_e32 v70, v70, v70
	v_max_f32_e32 v71, v71, v71
	v_max_f32_e32 v72, v72, v72
	v_max_f32_e32 v73, v73, v73
	v_max_f32_e32 v74, v74, v74
	v_max_f32_e32 v75, v75, v75
	v_max_f32_e32 v76, v76, v76
	v_max_f32_e32 v77, v77, v77
	v_max_f32_e32 v78, v78, v78
	v_max_f32_e32 v79, v79, v79
	v_max_f32_e32 v64, 0, v64
	v_max_f32_e32 v65, 0, v65
	v_max_f32_e32 v66, 0, v66
	v_max_f32_e32 v67, 0, v67
	v_max_f32_e32 v68, 0, v68
	v_max_f32_e32 v69, 0, v69
	v_max_f32_e32 v70, 0, v70
	v_max_f32_e32 v71, 0, v71
	v_max_f32_e32 v72, 0, v72
	v_max_f32_e32 v73, 0, v73
	v_max_f32_e32 v74, 0, v74
	v_max_f32_e32 v75, 0, v75
	v_max_f32_e32 v76, 0, v76
	v_max_f32_e32 v77, 0, v77
	v_max_f32_e32 v78, 0, v78
	v_max_f32_e32 v79, 0, v79
	v_pk_mul_f32 v[64:65], v[64:65], v[64:65]
	v_pk_mul_f32 v[66:67], v[66:67], v[66:67]
	v_pk_mul_f32 v[68:69], v[68:69], v[68:69]
	v_pk_mul_f32 v[70:71], v[70:71], v[70:71]
	v_pk_mul_f32 v[72:73], v[72:73], v[72:73]
	v_pk_mul_f32 v[74:75], v[74:75], v[74:75]
	v_pk_mul_f32 v[76:77], v[76:77], v[76:77]
	v_pk_mul_f32 v[78:79], v[78:79], v[78:79]
	v_cvt_pk_bf16_f32 v76, v76, v77
	v_cvt_pk_bf16_f32 v77, v78, v79
	v_cvt_pk_bf16_f32 v78, v72, v73
	v_cvt_pk_bf16_f32 v79, v74, v75
	v_cvt_pk_bf16_f32 v68, v68, v69
	v_cvt_pk_bf16_f32 v69, v70, v71
	v_cvt_pk_bf16_f32 v70, v64, v65
	v_cvt_pk_bf16_f32 v71, v66, v67
	s_nop 1
	v_permlane16_swap_b32_e32 v76, v78
	v_permlane16_swap_b32_e32 v77, v79
	v_permlane16_swap_b32_e32 v68, v70
	v_permlane16_swap_b32_e32 v69, v71
	v_lshl_add_u64 v[130:131], v[132:133], 0, vcc
	s_nop 0
	global_store_dwordx4 v[132:133], v[76:79], off
	global_store_dwordx4 v[132:133], v[68:71], off offset:64
	v_max_f32_e32 v48, v48, v48
	v_max_f32_e32 v49, v49, v49
	v_max_f32_e32 v50, v50, v50
	v_max_f32_e32 v51, v51, v51
	v_max_f32_e32 v52, v52, v52
	v_max_f32_e32 v53, v53, v53
	v_max_f32_e32 v54, v54, v54
	v_max_f32_e32 v55, v55, v55
	v_max_f32_e32 v56, v56, v56
	v_max_f32_e32 v57, v57, v57
	v_max_f32_e32 v58, v58, v58
	v_max_f32_e32 v59, v59, v59
	v_max_f32_e32 v60, v60, v60
	v_max_f32_e32 v61, v61, v61
	v_max_f32_e32 v62, v62, v62
	v_max_f32_e32 v63, v63, v63
	v_max_f32_e32 v48, 0, v48
	v_max_f32_e32 v49, 0, v49
	v_max_f32_e32 v50, 0, v50
	v_max_f32_e32 v51, 0, v51
	v_max_f32_e32 v52, 0, v52
	v_max_f32_e32 v53, 0, v53
	v_max_f32_e32 v54, 0, v54
	v_max_f32_e32 v55, 0, v55
	v_max_f32_e32 v56, 0, v56
	v_max_f32_e32 v57, 0, v57
	v_max_f32_e32 v58, 0, v58
	v_max_f32_e32 v59, 0, v59
	v_max_f32_e32 v60, 0, v60
	v_max_f32_e32 v61, 0, v61
	v_max_f32_e32 v62, 0, v62
	v_max_f32_e32 v63, 0, v63
	v_pk_mul_f32 v[48:49], v[48:49], v[48:49]
	v_pk_mul_f32 v[50:51], v[50:51], v[50:51]
	v_pk_mul_f32 v[52:53], v[52:53], v[52:53]
	v_pk_mul_f32 v[54:55], v[54:55], v[54:55]
	v_pk_mul_f32 v[56:57], v[56:57], v[56:57]
	v_pk_mul_f32 v[58:59], v[58:59], v[58:59]
	v_pk_mul_f32 v[60:61], v[60:61], v[60:61]
	v_pk_mul_f32 v[62:63], v[62:63], v[62:63]
	v_cvt_pk_bf16_f32 v60, v60, v61
	v_cvt_pk_bf16_f32 v61, v62, v63
	v_cvt_pk_bf16_f32 v62, v56, v57
	v_cvt_pk_bf16_f32 v63, v58, v59
	v_cvt_pk_bf16_f32 v52, v52, v53
	v_cvt_pk_bf16_f32 v53, v54, v55
	v_cvt_pk_bf16_f32 v54, v48, v49
	v_cvt_pk_bf16_f32 v55, v50, v51
	s_nop 1
	v_permlane16_swap_b32_e32 v60, v62
	v_permlane16_swap_b32_e32 v61, v63
	v_permlane16_swap_b32_e32 v52, v54
	v_permlane16_swap_b32_e32 v53, v55
	v_lshl_add_u64 v[132:133], v[130:131], 0, vcc
	s_nop 0
	global_store_dwordx4 v[130:131], v[60:63], off
	global_store_dwordx4 v[130:131], v[52:55], off offset:64
	v_max_f32_e32 v32, v32, v32
	v_max_f32_e32 v33, v33, v33
	v_max_f32_e32 v34, v34, v34
	v_max_f32_e32 v35, v35, v35
	v_max_f32_e32 v36, v36, v36
	v_max_f32_e32 v37, v37, v37
	v_max_f32_e32 v38, v38, v38
	v_max_f32_e32 v39, v39, v39
	v_max_f32_e32 v40, v40, v40
	v_max_f32_e32 v41, v41, v41
	v_max_f32_e32 v42, v42, v42
	v_max_f32_e32 v43, v43, v43
	v_max_f32_e32 v44, v44, v44
	v_max_f32_e32 v45, v45, v45
	v_max_f32_e32 v46, v46, v46
	v_max_f32_e32 v47, v47, v47
	v_max_f32_e32 v32, 0, v32
	v_max_f32_e32 v33, 0, v33
;     __device__ __forceinline__ void fin(int m, int n, f32x4 v, f32x4, f32x4) const { horiz(m, n, v); }
;     __device__ __forceinline__ void fin(int m, int n, f32x4 v, f32x4, f32x4) const { horiz(m, n, v); }
; template <int MI, bool SWAP, class Epi> ...
;     ...
;     if (SWAP) {
; #pragma unroll
;         for (int i2 = 0; i2 < MI / 2; ++i2) {
;             f32x4 pa[2][4], pg[2][4];
; #pragma unroll
;             for (int ii = 0; ii < 2; ++ii)
; #pragma unroll
;                 for (int j = 0; j < 4; ++j) epi.pre(m0 + wr * (MI * 16) + (i2 * 2 + ii) * 16 + fr, n0 + wc * 64 + j * 16 + fq * 4, pa[ii][j], pg[ii][j]);
;             __builtin_amdgcn_sched_barrier(0);
; #pragma unroll
;             for (int ii = 0; ii < 2; ++ii)
; #pragma unroll
;                 for (int j = 0; j < 4; ++j) epi.fin(m0 + wr * (MI * 16) + (i2 * 2 + ii) * 16 + fr, n0 + wc * 64 + j * 16 + fq * 4, acc[i2 * 2 + ii][j], pa[ii][j], pg[ii][j]);
;         }
;     __device__ __forceinline__ void horiz(int m, int n, f32x4 v) const {
;         float a = fmaxf(v[0], 0.f), b = fmaxf(v[1], 0.f), c = fmaxf(v[2], 0.f), d = fmaxf(v[3], 0.f);
;         u32x2 w; w.x = pack2(a * a, b * b); w.y = pack2(c * c, d * d);
;         *(u32x2*)(HID + (size_t)m * DFF + n) = w;
;     }
	v_max_f32_e32 v34, 0, v34
	v_max_f32_e32 v35, 0, v35
	v_max_f32_e32 v36, 0, v36
	v_max_f32_e32 v37, 0, v37
	v_max_f32_e32 v38, 0, v38
	v_max_f32_e32 v39, 0, v39
	v_max_f32_e32 v40, 0, v40
	v_max_f32_e32 v41, 0, v41
	v_max_f32_e32 v42, 0, v42
	v_max_f32_e32 v43, 0, v43
	v_max_f32_e32 v44, 0, v44
	v_max_f32_e32 v45, 0, v45
	v_max_f32_e32 v46, 0, v46
	v_max_f32_e32 v47, 0, v47
	v_pk_mul_f32 v[32:33], v[32:33], v[32:33]
	v_pk_mul_f32 v[34:35], v[34:35], v[34:35]
	v_pk_mul_f32 v[36:37], v[36:37], v[36:37]
	v_pk_mul_f32 v[38:39], v[38:39], v[38:39]
	v_pk_mul_f32 v[40:41], v[40:41], v[40:41]
	v_pk_mul_f32 v[42:43], v[42:43], v[42:43]
	v_pk_mul_f32 v[44:45], v[44:45], v[44:45]
	v_pk_mul_f32 v[46:47], v[46:47], v[46:47]
	v_cvt_pk_bf16_f32 v44, v44, v45
	v_cvt_pk_bf16_f32 v45, v46, v47
	v_cvt_pk_bf16_f32 v46, v40, v41
	v_cvt_pk_bf16_f32 v47, v42, v43
	v_cvt_pk_bf16_f32 v36, v36, v37
	v_cvt_pk_bf16_f32 v37, v38, v39
	v_cvt_pk_bf16_f32 v38, v32, v33
	v_cvt_pk_bf16_f32 v39, v34, v35
	s_nop 1
	v_permlane16_swap_b32_e32 v44, v46
	v_permlane16_swap_b32_e32 v45, v47
	v_permlane16_swap_b32_e32 v36, v38
	v_permlane16_swap_b32_e32 v37, v39
	v_lshl_add_u64 v[130:131], v[132:133], 0, vcc
	s_nop 0
	global_store_dwordx4 v[132:133], v[44:47], off
	global_store_dwordx4 v[132:133], v[36:39], off offset:64
	v_max_f32_e32 v16, v16, v16
	v_max_f32_e32 v17, v17, v17
	v_max_f32_e32 v18, v18, v18
	v_max_f32_e32 v19, v19, v19
	v_max_f32_e32 v20, v20, v20
	v_max_f32_e32 v21, v21, v21
	v_max_f32_e32 v22, v22, v22
	v_max_f32_e32 v23, v23, v23
	v_max_f32_e32 v24, v24, v24
	v_max_f32_e32 v25, v25, v25
	v_max_f32_e32 v26, v26, v26
	v_max_f32_e32 v27, v27, v27
	v_max_f32_e32 v28, v28, v28
	v_max_f32_e32 v29, v29, v29
	v_max_f32_e32 v30, v30, v30
	v_max_f32_e32 v31, v31, v31
	v_max_f32_e32 v16, 0, v16
	v_max_f32_e32 v17, 0, v17
	v_max_f32_e32 v18, 0, v18
	v_max_f32_e32 v19, 0, v19
	v_max_f32_e32 v20, 0, v20
	v_max_f32_e32 v21, 0, v21
	v_max_f32_e32 v22, 0, v22
	v_max_f32_e32 v23, 0, v23
	v_max_f32_e32 v24, 0, v24
	v_max_f32_e32 v25, 0, v25
	v_max_f32_e32 v26, 0, v26
	v_max_f32_e32 v27, 0, v27
	v_max_f32_e32 v28, 0, v28
	v_max_f32_e32 v29, 0, v29
	v_max_f32_e32 v30, 0, v30
	v_max_f32_e32 v31, 0, v31
	v_pk_mul_f32 v[16:17], v[16:17], v[16:17]
	v_pk_mul_f32 v[18:19], v[18:19], v[18:19]
	v_pk_mul_f32 v[20:21], v[20:21], v[20:21]
	v_pk_mul_f32 v[22:23], v[22:23], v[22:23]
	v_pk_mul_f32 v[24:25], v[24:25], v[24:25]
	v_pk_mul_f32 v[26:27], v[26:27], v[26:27]
	v_pk_mul_f32 v[28:29], v[28:29], v[28:29]
	v_pk_mul_f32 v[30:31], v[30:31], v[30:31]
	v_cvt_pk_bf16_f32 v28, v28, v29
	v_cvt_pk_bf16_f32 v29, v30, v31
	v_cvt_pk_bf16_f32 v30, v24, v25
	v_cvt_pk_bf16_f32 v31, v26, v27
	v_cvt_pk_bf16_f32 v20, v20, v21
	v_cvt_pk_bf16_f32 v21, v22, v23
	v_cvt_pk_bf16_f32 v22, v16, v17
	v_cvt_pk_bf16_f32 v23, v18, v19
	s_nop 1
	v_permlane16_swap_b32_e32 v28, v30
	v_permlane16_swap_b32_e32 v29, v31
	v_permlane16_swap_b32_e32 v20, v22
	v_permlane16_swap_b32_e32 v21, v23
	v_lshl_add_u64 v[132:133], v[130:131], 0, vcc
	s_nop 0
	global_store_dwordx4 v[130:131], v[28:31], off
	global_store_dwordx4 v[130:131], v[20:23], off offset:64
	v_max_f32_e32 v0, v0, v0
	v_max_f32_e32 v1, v1, v1
	v_max_f32_e32 v2, v2, v2
	v_max_f32_e32 v3, v3, v3
	v_max_f32_e32 v4, v4, v4
	v_max_f32_e32 v5, v5, v5
	v_max_f32_e32 v6, v6, v6
	v_max_f32_e32 v7, v7, v7
	v_max_f32_e32 v8, v8, v8
	v_max_f32_e32 v9, v9, v9
	v_max_f32_e32 v10, v10, v10
	v_max_f32_e32 v11, v11, v11
	v_max_f32_e32 v12, v12, v12
	v_max_f32_e32 v13, v13, v13
	v_max_f32_e32 v14, v14, v14
	v_max_f32_e32 v15, v15, v15
	v_max_f32_e32 v0, 0, v0
	v_max_f32_e32 v1, 0, v1
	v_max_f32_e32 v2, 0, v2
	v_max_f32_e32 v3, 0, v3
	v_max_f32_e32 v4, 0, v4
	v_max_f32_e32 v5, 0, v5
	v_max_f32_e32 v6, 0, v6
	v_max_f32_e32 v7, 0, v7
	v_max_f32_e32 v8, 0, v8
	v_max_f32_e32 v9, 0, v9
	v_max_f32_e32 v10, 0, v10
	v_max_f32_e32 v11, 0, v11
	v_max_f32_e32 v12, 0, v12
	v_max_f32_e32 v13, 0, v13
	v_max_f32_e32 v14, 0, v14
	v_max_f32_e32 v15, 0, v15
	v_pk_mul_f32 v[0:1], v[0:1], v[0:1]
	v_pk_mul_f32 v[2:3], v[2:3], v[2:3]
	v_pk_mul_f32 v[4:5], v[4:5], v[4:5]
	v_pk_mul_f32 v[6:7], v[6:7], v[6:7]
	v_pk_mul_f32 v[8:9], v[8:9], v[8:9]
	v_pk_mul_f32 v[10:11], v[10:11], v[10:11]
	v_pk_mul_f32 v[12:13], v[12:13], v[12:13]
	v_pk_mul_f32 v[14:15], v[14:15], v[14:15]
	v_cvt_pk_bf16_f32 v12, v12, v13
	v_cvt_pk_bf16_f32 v13, v14, v15
	v_cvt_pk_bf16_f32 v14, v8, v9
	v_cvt_pk_bf16_f32 v15, v10, v11
	v_cvt_pk_bf16_f32 v4, v4, v5
	v_cvt_pk_bf16_f32 v5, v6, v7
	v_cvt_pk_bf16_f32 v6, v0, v1
	v_cvt_pk_bf16_f32 v7, v2, v3
	s_nop 1
	v_permlane16_swap_b32_e32 v12, v14
	v_permlane16_swap_b32_e32 v13, v15
	v_permlane16_swap_b32_e32 v4, v6
	v_permlane16_swap_b32_e32 v5, v7
	s_nop 0
	global_store_dwordx4 v[132:133], v[12:15], off
	global_store_dwordx4 v[132:133], v[4:7], off offset:64
	s_andn2_b64 vcc, exec, s[2:3]
	s_mov_b64 s[22:23], -1
	s_cbranch_vccz .LBB0_2207
